# T21 / lever 2: attention epilogue stores widened with v_permlane32_swap: 8x global_store_dwordx2 -> 4x global_store_dwordx4 per wave (same bytes, same addresses)
# speedup vs baseline: 1.0118x; 1.0085x over previous
; __device__ __forceinline__ unsigned cvt_pk_bf16(float lo, float hi) { const f32x2 v = {lo, hi}; const bf16x2_t b = __builtin_convertvector(v, bf16x2_t); return __builtin_bit_cast(unsigned, b); }
; __device__ __forceinline__ void attn_phase(LAS unsigned char* lds, const bf16_t* Q, const bf16_t* Kb, const bf16_t* Vt, bf16_t* O, const float* relb, const float* qn, const float* kn, int vcu, int G) {
;     ...
;         const float lt = lrun + __shfl_xor(lrun, 32), il = 1.f / lt;
;         bf16_t* op = O + (rowbase + (size_t)qb * 256 + w * 32 + r32) * D + h * 64 + 4 * hi;
; #pragma unroll
;         for (int gq = 0; gq < 4; ++gq) {
;             u32x2 a; a.x = cvt_pk_bf16(o0[4 * gq] * il, o0[4 * gq + 1] * il); a.y = cvt_pk_bf16(o0[4 * gq + 2] * il, o0[4 * gq + 3] * il);
;             u32x2 c; c.x = cvt_pk_bf16(o1[4 * gq] * il, o1[4 * gq + 1] * il); c.y = cvt_pk_bf16(o1[4 * gq + 2] * il, o1[4 * gq + 3] * il);
;             *(u32x2*)(op + 8 * gq) = a; *(u32x2*)(op + 32 + 8 * gq) = c;
;         }
.LBB0_435:
	ds_bpermute_b32 v1, v147, v131
	v_readlane_b32 s12, v252, 57
	v_readlane_b32 s13, v252, 58
	s_lshl_b32 s54, s35, 1
	v_mov_b32_e32 v135, v0
	s_waitcnt lgkmcnt(0)
	v_add_f32_e32 v1, v131, v1
	v_div_scale_f32 v4, s[18:19], v1, v1, 1.0
	v_rcp_f32_e32 v5, v4
	v_div_scale_f32 v6, vcc, 1.0, v1, 1.0
	v_lshl_add_u64 v[2:3], v[136:137], 1, s[12:13]
	v_fma_f32 v7, -v4, v5, 1.0
	v_fmac_f32_e32 v5, v7, v5
	v_mul_f32_e32 v7, v6, v5
	v_fma_f32 v8, -v4, v7, v6
	v_fmac_f32_e32 v7, v8, v5
	v_fma_f32 v4, -v4, v7, v6
	v_div_fmas_f32 v4, v4, v5, v7
	v_div_fixup_f32 v4, v4, v1, 1.0
	v_lshl_add_u64 v[2:3], v[2:3], 0, s[54:55]
	v_lshl_add_u64 v[2:3], v[2:3], 0, v[134:135]
	v_mbcnt_lo_u32_b32 v10, -1, 0
	v_lshrrev_b32_e32 v10, 5, v10
	v_lshlrev_b32_e32 v10, 3, v10
	v_mov_b32_e32 v11, 0
	v_lshl_add_u64 v[2:3], v[2:3], 0, v[10:11]
	v_pk_mul_f32 v[6:7], v[64:65], v[4:5] op_sel_hi:[1,0]
	v_pk_mul_f32 v[8:9], v[66:67], v[4:5] op_sel_hi:[1,0]
	v_cvt_pk_bf16_f32 v6, v6, v7
	v_cvt_pk_bf16_f32 v7, v8, v9
	v_pk_mul_f32 v[8:9], v[68:69], v[4:5] op_sel_hi:[1,0]
	v_pk_mul_f32 v[10:11], v[70:71], v[4:5] op_sel_hi:[1,0]
	v_cvt_pk_bf16_f32 v8, v8, v9
	v_cvt_pk_bf16_f32 v9, v10, v11
	s_nop 1
	v_permlane32_swap_b32_e32 v6, v8
	v_permlane32_swap_b32_e32 v7, v9
	global_store_dwordx4 v[2:3], v[6:9], off
	s_nop 1
	v_pk_mul_f32 v[6:7], v[72:73], v[4:5] op_sel_hi:[1,0]
	v_pk_mul_f32 v[8:9], v[74:75], v[4:5] op_sel_hi:[1,0]
	v_cvt_pk_bf16_f32 v6, v6, v7
	v_cvt_pk_bf16_f32 v7, v8, v9
	v_pk_mul_f32 v[8:9], v[76:77], v[4:5] op_sel_hi:[1,0]
	v_pk_mul_f32 v[10:11], v[78:79], v[4:5] op_sel_hi:[1,0]
	v_cvt_pk_bf16_f32 v8, v8, v9
	v_cvt_pk_bf16_f32 v9, v10, v11
	s_nop 1
	v_permlane32_swap_b32_e32 v6, v8
	v_permlane32_swap_b32_e32 v7, v9
	global_store_dwordx4 v[2:3], v[6:9], off offset:32
	s_nop 1
	v_pk_mul_f32 v[6:7], v[48:49], v[4:5] op_sel_hi:[1,0]
	v_pk_mul_f32 v[8:9], v[50:51], v[4:5] op_sel_hi:[1,0]
	v_cvt_pk_bf16_f32 v6, v6, v7
	v_cvt_pk_bf16_f32 v7, v8, v9
	v_pk_mul_f32 v[8:9], v[52:53], v[4:5] op_sel_hi:[1,0]
	v_pk_mul_f32 v[10:11], v[54:55], v[4:5] op_sel_hi:[1,0]
	v_cvt_pk_bf16_f32 v8, v8, v9
	v_cvt_pk_bf16_f32 v9, v10, v11
	s_nop 1
	v_permlane32_swap_b32_e32 v6, v8
	v_permlane32_swap_b32_e32 v7, v9
	global_store_dwordx4 v[2:3], v[6:9], off offset:64
	s_nop 1
	v_pk_mul_f32 v[6:7], v[56:57], v[4:5] op_sel_hi:[1,0]
	v_pk_mul_f32 v[8:9], v[58:59], v[4:5] op_sel_hi:[1,0]
	v_cvt_pk_bf16_f32 v6, v6, v7
	v_cvt_pk_bf16_f32 v7, v8, v9
	v_pk_mul_f32 v[8:9], v[60:61], v[4:5] op_sel_hi:[1,0]
	v_pk_mul_f32 v[10:11], v[62:63], v[4:5] op_sel_hi:[1,0]
	v_cvt_pk_bf16_f32 v8, v8, v9
	v_cvt_pk_bf16_f32 v9, v10, v11
	s_add_i32 s34, s34, s56
	s_add_i32 s30, s30, s56
	v_permlane32_swap_b32_e32 v6, v8
	v_permlane32_swap_b32_e32 v7, v9
	s_cmpk_lt_i32 s34, 0x800
	global_store_dwordx4 v[2:3], v[6:9], off offset:96
	s_cbranch_scc0 .LBB0_473
